# write-through GEMM epilogue stores combined with GU cross-tile prefetch (next tile's first loads issued before the stores so load waits do not include write-through store acks)
# baseline (speedup 1.0000x reference)
.Lg16_gu_np:
	s_nop 7
	s_nop 1
	v_and_b32_e32 v163, 63, v179
	v_lshrrev_b32_e32 v164, 6, v179
	s_lshl_b32 s14, s7, 3
	s_mul_hi_u32 s15, s14, 0x2c000
	s_mul_i32 s14, s14, 0x2c000
	s_lshl_b32 s16, s0, 12
	s_add_u32 s12, s66, s14
	s_addc_u32 s13, s67, s15
	s_add_u32 s12, s12, s16
	s_addc_u32 s13, s13, 0
	v_and_b32_e32 v165, 15, v163
	v_lshlrev_b32_e32 v166, 4, v165
	v_lshrrev_b32_e32 v165, 4, v163
	v_lshl_add_u32 v166, v165, 9, v166
	v_mul_u32_u24_e32 v165, 0x58000, v164
	v_add_u32_e32 v166, v166, v165
	v_add_u32_e32 v167, 0x2c000, v166
	v_mul_f32_e32 v196, 0xbfb8aa3b, v112
	v_mul_f32_e32 v197, 0xbfb8aa3b, v113
	v_mul_f32_e32 v198, 0xbfb8aa3b, v114
	v_mul_f32_e32 v199, 0xbfb8aa3b, v115
	v_mul_f32_e32 v200, 0xbfb8aa3b, v116
	v_mul_f32_e32 v201, 0xbfb8aa3b, v117
	v_mul_f32_e32 v202, 0xbfb8aa3b, v118
	v_mul_f32_e32 v203, 0xbfb8aa3b, v119
	v_exp_f32_e32 v196, v196
	v_exp_f32_e32 v197, v197
	v_exp_f32_e32 v198, v198
	v_exp_f32_e32 v199, v199
	v_exp_f32_e32 v200, v200
	v_exp_f32_e32 v201, v201
	v_exp_f32_e32 v202, v202
	v_exp_f32_e32 v203, v203
	v_add_f32_e32 v196, 1.0, v196
	v_add_f32_e32 v197, 1.0, v197
	v_add_f32_e32 v198, 1.0, v198
	v_add_f32_e32 v199, 1.0, v199
	v_add_f32_e32 v200, 1.0, v200
	v_add_f32_e32 v201, 1.0, v201
	v_add_f32_e32 v202, 1.0, v202
	v_add_f32_e32 v203, 1.0, v203
	v_rcp_f32_e32 v196, v196
	v_rcp_f32_e32 v197, v197
	v_rcp_f32_e32 v198, v198
	v_rcp_f32_e32 v199, v199
	v_rcp_f32_e32 v200, v200
	v_rcp_f32_e32 v201, v201
	v_rcp_f32_e32 v202, v202
	v_rcp_f32_e32 v203, v203
	v_mul_f32_e32 v196, v112, v196
	v_mul_f32_e32 v197, v113, v197
	v_mul_f32_e32 v198, v114, v198
	v_mul_f32_e32 v199, v115, v199
	v_mul_f32_e32 v200, v116, v200
	v_mul_f32_e32 v201, v117, v201
	v_mul_f32_e32 v202, v118, v202
	v_mul_f32_e32 v203, v119, v203
	v_mul_f32_e32 v196, v96, v196
	v_mul_f32_e32 v197, v97, v197
	v_mul_f32_e32 v198, v98, v198
	v_mul_f32_e32 v199, v99, v199
	v_mul_f32_e32 v200, v100, v200
	v_mul_f32_e32 v201, v101, v201
	v_mul_f32_e32 v202, v102, v202
	v_mul_f32_e32 v203, v103, v203
	v_cvt_pk_bf16_f32 v204, v196, v197
	v_cvt_pk_bf16_f32 v205, v198, v199
	v_cvt_pk_bf16_f32 v206, v200, v201
	v_cvt_pk_bf16_f32 v207, v202, v203
	global_store_dwordx4 v166, v[204:207], s[12:13] sc0 sc1
	v_mul_f32_e32 v196, 0xbfb8aa3b, v120
	v_mul_f32_e32 v197, 0xbfb8aa3b, v121
	v_mul_f32_e32 v198, 0xbfb8aa3b, v122
	v_mul_f32_e32 v199, 0xbfb8aa3b, v123
	v_mul_f32_e32 v200, 0xbfb8aa3b, v124
	v_mul_f32_e32 v201, 0xbfb8aa3b, v125
	v_mul_f32_e32 v202, 0xbfb8aa3b, v126
	v_mul_f32_e32 v203, 0xbfb8aa3b, v127
	v_exp_f32_e32 v196, v196
	v_exp_f32_e32 v197, v197
	v_exp_f32_e32 v198, v198
	v_exp_f32_e32 v199, v199
	v_exp_f32_e32 v200, v200
	v_exp_f32_e32 v201, v201
	v_exp_f32_e32 v202, v202
	v_exp_f32_e32 v203, v203
	v_add_f32_e32 v196, 1.0, v196
	v_add_f32_e32 v197, 1.0, v197
	v_add_f32_e32 v198, 1.0, v198
	v_add_f32_e32 v199, 1.0, v199
	v_add_f32_e32 v200, 1.0, v200
	v_add_f32_e32 v201, 1.0, v201
	v_add_f32_e32 v202, 1.0, v202
	v_add_f32_e32 v203, 1.0, v203
	v_rcp_f32_e32 v196, v196
	v_rcp_f32_e32 v197, v197
	v_rcp_f32_e32 v198, v198
	v_rcp_f32_e32 v199, v199
	v_rcp_f32_e32 v200, v200
	v_rcp_f32_e32 v201, v201
	v_rcp_f32_e32 v202, v202
	v_rcp_f32_e32 v203, v203
	v_mul_f32_e32 v196, v120, v196
	v_mul_f32_e32 v197, v121, v197
	v_mul_f32_e32 v198, v122, v198
	v_mul_f32_e32 v199, v123, v199
	v_mul_f32_e32 v200, v124, v200
	v_mul_f32_e32 v201, v125, v201
	v_mul_f32_e32 v202, v126, v202
	v_mul_f32_e32 v203, v127, v203
	v_mul_f32_e32 v196, v104, v196
	v_mul_f32_e32 v197, v105, v197
	v_mul_f32_e32 v198, v106, v198
	v_mul_f32_e32 v199, v107, v199
	v_mul_f32_e32 v200, v108, v200
	v_mul_f32_e32 v201, v109, v201
	v_mul_f32_e32 v202, v110, v202
	v_mul_f32_e32 v203, v111, v203
	v_cvt_pk_bf16_f32 v242, v196, v197
	v_cvt_pk_bf16_f32 v243, v198, v199
	v_cvt_pk_bf16_f32 v244, v200, v201
	v_cvt_pk_bf16_f32 v245, v202, v203
	global_store_dwordx4 v166, v[242:245], s[12:13] offset:256 sc0 sc1
	v_mul_f32_e32 v196, 0xbfb8aa3b, v80
	v_mul_f32_e32 v197, 0xbfb8aa3b, v81
	v_mul_f32_e32 v198, 0xbfb8aa3b, v82
	v_mul_f32_e32 v199, 0xbfb8aa3b, v83
	v_mul_f32_e32 v200, 0xbfb8aa3b, v84
	v_mul_f32_e32 v201, 0xbfb8aa3b, v85
	v_mul_f32_e32 v202, 0xbfb8aa3b, v86
	v_mul_f32_e32 v203, 0xbfb8aa3b, v87
	v_exp_f32_e32 v196, v196
	v_exp_f32_e32 v197, v197
	v_exp_f32_e32 v198, v198
	v_exp_f32_e32 v199, v199
	v_exp_f32_e32 v200, v200
	v_exp_f32_e32 v201, v201
	v_exp_f32_e32 v202, v202
	v_exp_f32_e32 v203, v203
	v_add_f32_e32 v196, 1.0, v196
	v_add_f32_e32 v197, 1.0, v197
	v_add_f32_e32 v198, 1.0, v198
	v_add_f32_e32 v199, 1.0, v199
	v_add_f32_e32 v200, 1.0, v200
	v_add_f32_e32 v201, 1.0, v201
	v_add_f32_e32 v202, 1.0, v202
	v_add_f32_e32 v203, 1.0, v203
	v_rcp_f32_e32 v196, v196
	v_rcp_f32_e32 v197, v197
	v_rcp_f32_e32 v198, v198
	v_rcp_f32_e32 v199, v199
	v_rcp_f32_e32 v200, v200
	v_rcp_f32_e32 v201, v201
	v_rcp_f32_e32 v202, v202
	v_rcp_f32_e32 v203, v203
	v_mul_f32_e32 v196, v80, v196
	v_mul_f32_e32 v197, v81, v197
	v_mul_f32_e32 v198, v82, v198
	v_mul_f32_e32 v199, v83, v199
	v_mul_f32_e32 v200, v84, v200
	v_mul_f32_e32 v201, v85, v201
	v_mul_f32_e32 v202, v86, v202
	v_mul_f32_e32 v203, v87, v203
	v_mul_f32_e32 v196, v64, v196
	v_mul_f32_e32 v197, v65, v197
	v_mul_f32_e32 v198, v66, v198
	v_mul_f32_e32 v199, v67, v199
	v_mul_f32_e32 v200, v68, v200
	v_mul_f32_e32 v201, v69, v201
	v_mul_f32_e32 v202, v70, v202
	v_mul_f32_e32 v203, v71, v203
	v_cvt_pk_bf16_f32 v204, v196, v197
	v_cvt_pk_bf16_f32 v205, v198, v199
	v_cvt_pk_bf16_f32 v206, v200, v201
	v_cvt_pk_bf16_f32 v207, v202, v203
	global_store_dwordx4 v167, v[204:207], s[12:13] sc0 sc1
	v_mul_f32_e32 v196, 0xbfb8aa3b, v88
	v_mul_f32_e32 v197, 0xbfb8aa3b, v89
	v_mul_f32_e32 v198, 0xbfb8aa3b, v90
	v_mul_f32_e32 v199, 0xbfb8aa3b, v91
	v_mul_f32_e32 v200, 0xbfb8aa3b, v92
	v_mul_f32_e32 v201, 0xbfb8aa3b, v93
	v_mul_f32_e32 v202, 0xbfb8aa3b, v94
	v_mul_f32_e32 v203, 0xbfb8aa3b, v95
	v_exp_f32_e32 v196, v196
	v_exp_f32_e32 v197, v197
	v_exp_f32_e32 v198, v198
	v_exp_f32_e32 v199, v199
	v_exp_f32_e32 v200, v200
	v_exp_f32_e32 v201, v201
	v_exp_f32_e32 v202, v202
	v_exp_f32_e32 v203, v203
	v_add_f32_e32 v196, 1.0, v196
	v_add_f32_e32 v197, 1.0, v197
	v_add_f32_e32 v198, 1.0, v198
	v_add_f32_e32 v199, 1.0, v199
	v_add_f32_e32 v200, 1.0, v200
	v_add_f32_e32 v201, 1.0, v201
	v_add_f32_e32 v202, 1.0, v202
	v_add_f32_e32 v203, 1.0, v203
	v_rcp_f32_e32 v196, v196
	v_rcp_f32_e32 v197, v197
	v_rcp_f32_e32 v198, v198
	v_rcp_f32_e32 v199, v199
	v_rcp_f32_e32 v200, v200
	v_rcp_f32_e32 v201, v201
	v_rcp_f32_e32 v202, v202
	v_rcp_f32_e32 v203, v203
	v_mul_f32_e32 v196, v88, v196
	v_mul_f32_e32 v197, v89, v197
	v_mul_f32_e32 v198, v90, v198
	v_mul_f32_e32 v199, v91, v199
	v_mul_f32_e32 v200, v92, v200
	v_mul_f32_e32 v201, v93, v201
	v_mul_f32_e32 v202, v94, v202
	v_mul_f32_e32 v203, v95, v203
	v_mul_f32_e32 v196, v72, v196
	v_mul_f32_e32 v197, v73, v197
	v_mul_f32_e32 v198, v74, v198
	v_mul_f32_e32 v199, v75, v199
	v_mul_f32_e32 v200, v76, v200
	v_mul_f32_e32 v201, v77, v201
	v_mul_f32_e32 v202, v78, v202
	v_mul_f32_e32 v203, v79, v203
	v_cvt_pk_bf16_f32 v242, v196, v197
	v_cvt_pk_bf16_f32 v243, v198, v199
	v_cvt_pk_bf16_f32 v244, v200, v201
	v_cvt_pk_bf16_f32 v245, v202, v203
	global_store_dwordx4 v167, v[242:245], s[12:13] offset:256 sc0 sc1
	v_mul_f32_e32 v196, 0xbfb8aa3b, v48
	v_mul_f32_e32 v197, 0xbfb8aa3b, v49
	v_mul_f32_e32 v198, 0xbfb8aa3b, v50
	v_mul_f32_e32 v199, 0xbfb8aa3b, v51
	v_mul_f32_e32 v200, 0xbfb8aa3b, v52
	v_mul_f32_e32 v201, 0xbfb8aa3b, v53
	v_mul_f32_e32 v202, 0xbfb8aa3b, v54
	v_mul_f32_e32 v203, 0xbfb8aa3b, v55
	v_exp_f32_e32 v196, v196
	v_exp_f32_e32 v197, v197
	v_exp_f32_e32 v198, v198
	v_exp_f32_e32 v199, v199
	v_exp_f32_e32 v200, v200
	v_exp_f32_e32 v201, v201
	v_exp_f32_e32 v202, v202
	v_exp_f32_e32 v203, v203
	v_add_f32_e32 v196, 1.0, v196
	v_add_f32_e32 v197, 1.0, v197
	v_add_f32_e32 v198, 1.0, v198
	v_add_f32_e32 v199, 1.0, v199
	v_add_f32_e32 v200, 1.0, v200
	v_add_f32_e32 v201, 1.0, v201
	v_add_f32_e32 v202, 1.0, v202
	v_add_f32_e32 v203, 1.0, v203
	v_rcp_f32_e32 v196, v196
	v_rcp_f32_e32 v197, v197
	v_rcp_f32_e32 v198, v198
	v_rcp_f32_e32 v199, v199
	v_rcp_f32_e32 v200, v200
	v_rcp_f32_e32 v201, v201
	v_rcp_f32_e32 v202, v202
	v_rcp_f32_e32 v203, v203
	v_mul_f32_e32 v196, v48, v196
	v_mul_f32_e32 v197, v49, v197
	v_mul_f32_e32 v198, v50, v198
	v_mul_f32_e32 v199, v51, v199
	v_mul_f32_e32 v200, v52, v200
	v_mul_f32_e32 v201, v53, v201
	v_mul_f32_e32 v202, v54, v202
	v_mul_f32_e32 v203, v55, v203
	v_mul_f32_e32 v196, v32, v196
	v_mul_f32_e32 v197, v33, v197
	v_mul_f32_e32 v198, v34, v198
	v_mul_f32_e32 v199, v35, v199
	v_mul_f32_e32 v200, v36, v200
	v_mul_f32_e32 v201, v37, v201
	v_mul_f32_e32 v202, v38, v202
	v_mul_f32_e32 v203, v39, v203
	v_cvt_pk_bf16_f32 v204, v196, v197
	v_cvt_pk_bf16_f32 v205, v198, v199
	v_cvt_pk_bf16_f32 v206, v200, v201
	v_cvt_pk_bf16_f32 v207, v202, v203
	global_store_dwordx4 v166, v[204:207], s[12:13] offset:2048 sc0 sc1
	v_mul_f32_e32 v196, 0xbfb8aa3b, v56
	v_mul_f32_e32 v197, 0xbfb8aa3b, v57
	v_mul_f32_e32 v198, 0xbfb8aa3b, v58
	v_mul_f32_e32 v199, 0xbfb8aa3b, v59
	v_mul_f32_e32 v200, 0xbfb8aa3b, v60
	v_mul_f32_e32 v201, 0xbfb8aa3b, v61
	v_mul_f32_e32 v202, 0xbfb8aa3b, v62
	v_mul_f32_e32 v203, 0xbfb8aa3b, v63
	v_exp_f32_e32 v196, v196
	v_exp_f32_e32 v197, v197
	v_exp_f32_e32 v198, v198
	v_exp_f32_e32 v199, v199
	v_exp_f32_e32 v200, v200
	v_exp_f32_e32 v201, v201
	v_exp_f32_e32 v202, v202
	v_exp_f32_e32 v203, v203
	v_add_f32_e32 v196, 1.0, v196
	v_add_f32_e32 v197, 1.0, v197
	v_add_f32_e32 v198, 1.0, v198
	v_add_f32_e32 v199, 1.0, v199
	v_add_f32_e32 v200, 1.0, v200
	v_add_f32_e32 v201, 1.0, v201
	v_add_f32_e32 v202, 1.0, v202
	v_add_f32_e32 v203, 1.0, v203
	v_rcp_f32_e32 v196, v196
	v_rcp_f32_e32 v197, v197
	v_rcp_f32_e32 v198, v198
	v_rcp_f32_e32 v199, v199
	v_rcp_f32_e32 v200, v200
	v_rcp_f32_e32 v201, v201
	v_rcp_f32_e32 v202, v202
	v_rcp_f32_e32 v203, v203
	v_mul_f32_e32 v196, v56, v196
	v_mul_f32_e32 v197, v57, v197
	v_mul_f32_e32 v198, v58, v198
	v_mul_f32_e32 v199, v59, v199
	v_mul_f32_e32 v200, v60, v200
	v_mul_f32_e32 v201, v61, v201
	v_mul_f32_e32 v202, v62, v202
	v_mul_f32_e32 v203, v63, v203
	v_mul_f32_e32 v196, v40, v196
	v_mul_f32_e32 v197, v41, v197
	v_mul_f32_e32 v198, v42, v198
	v_mul_f32_e32 v199, v43, v199
	v_mul_f32_e32 v200, v44, v200
	v_mul_f32_e32 v201, v45, v201
	v_mul_f32_e32 v202, v46, v202
	v_mul_f32_e32 v203, v47, v203
	v_cvt_pk_bf16_f32 v242, v196, v197
	v_cvt_pk_bf16_f32 v243, v198, v199
	v_cvt_pk_bf16_f32 v244, v200, v201
	v_cvt_pk_bf16_f32 v245, v202, v203
	global_store_dwordx4 v166, v[242:245], s[12:13] offset:2304 sc0 sc1
	v_mul_f32_e32 v196, 0xbfb8aa3b, v16
	v_mul_f32_e32 v197, 0xbfb8aa3b, v17
	v_mul_f32_e32 v198, 0xbfb8aa3b, v18
	v_mul_f32_e32 v199, 0xbfb8aa3b, v19
	v_mul_f32_e32 v200, 0xbfb8aa3b, v20
	v_mul_f32_e32 v201, 0xbfb8aa3b, v21
	v_mul_f32_e32 v202, 0xbfb8aa3b, v22
	v_mul_f32_e32 v203, 0xbfb8aa3b, v23
	v_exp_f32_e32 v196, v196
	v_exp_f32_e32 v197, v197
	v_exp_f32_e32 v198, v198
	v_exp_f32_e32 v199, v199
	v_exp_f32_e32 v200, v200
	v_exp_f32_e32 v201, v201
	v_exp_f32_e32 v202, v202
	v_exp_f32_e32 v203, v203
	v_add_f32_e32 v196, 1.0, v196
	v_add_f32_e32 v197, 1.0, v197
	v_add_f32_e32 v198, 1.0, v198
	v_add_f32_e32 v199, 1.0, v199
	v_add_f32_e32 v200, 1.0, v200
	v_add_f32_e32 v201, 1.0, v201
	v_add_f32_e32 v202, 1.0, v202
	v_add_f32_e32 v203, 1.0, v203
	v_rcp_f32_e32 v196, v196
	v_rcp_f32_e32 v197, v197
	v_rcp_f32_e32 v198, v198
	v_rcp_f32_e32 v199, v199
	v_rcp_f32_e32 v200, v200
	v_rcp_f32_e32 v201, v201
	v_rcp_f32_e32 v202, v202
	v_rcp_f32_e32 v203, v203
	v_mul_f32_e32 v196, v16, v196
	v_mul_f32_e32 v197, v17, v197
	v_mul_f32_e32 v198, v18, v198
	v_mul_f32_e32 v199, v19, v199
	v_mul_f32_e32 v200, v20, v200
	v_mul_f32_e32 v201, v21, v201
	v_mul_f32_e32 v202, v22, v202
	v_mul_f32_e32 v203, v23, v203
	v_mul_f32_e32 v196, v0, v196
	v_mul_f32_e32 v197, v1, v197
	v_mul_f32_e32 v198, v2, v198
	v_mul_f32_e32 v199, v3, v199
	v_mul_f32_e32 v200, v4, v200
	v_mul_f32_e32 v201, v5, v201
	v_mul_f32_e32 v202, v6, v202
	v_mul_f32_e32 v203, v7, v203
	v_cvt_pk_bf16_f32 v204, v196, v197
	v_cvt_pk_bf16_f32 v205, v198, v199
	v_cvt_pk_bf16_f32 v206, v200, v201
	v_cvt_pk_bf16_f32 v207, v202, v203
	global_store_dwordx4 v167, v[204:207], s[12:13] offset:2048 sc0 sc1
	v_mul_f32_e32 v196, 0xbfb8aa3b, v24
	v_mul_f32_e32 v197, 0xbfb8aa3b, v25
	v_mul_f32_e32 v198, 0xbfb8aa3b, v26
	v_mul_f32_e32 v199, 0xbfb8aa3b, v27
	v_mul_f32_e32 v200, 0xbfb8aa3b, v28
	v_mul_f32_e32 v201, 0xbfb8aa3b, v29
	v_mul_f32_e32 v202, 0xbfb8aa3b, v30
	v_mul_f32_e32 v203, 0xbfb8aa3b, v31
	v_exp_f32_e32 v196, v196
	v_exp_f32_e32 v197, v197
	v_exp_f32_e32 v198, v198
	v_exp_f32_e32 v199, v199
	v_exp_f32_e32 v200, v200
	v_exp_f32_e32 v201, v201
	v_exp_f32_e32 v202, v202
	v_exp_f32_e32 v203, v203
	v_add_f32_e32 v196, 1.0, v196
	v_add_f32_e32 v197, 1.0, v197
	v_add_f32_e32 v198, 1.0, v198
	v_add_f32_e32 v199, 1.0, v199
	v_add_f32_e32 v200, 1.0, v200
	v_add_f32_e32 v201, 1.0, v201
	v_add_f32_e32 v202, 1.0, v202
	v_add_f32_e32 v203, 1.0, v203
	v_rcp_f32_e32 v196, v196
	v_rcp_f32_e32 v197, v197
	v_rcp_f32_e32 v198, v198
	v_rcp_f32_e32 v199, v199
	v_rcp_f32_e32 v200, v200
	v_rcp_f32_e32 v201, v201
	v_rcp_f32_e32 v202, v202
	v_rcp_f32_e32 v203, v203
	v_mul_f32_e32 v196, v24, v196
	v_mul_f32_e32 v197, v25, v197
	v_mul_f32_e32 v198, v26, v198
	v_mul_f32_e32 v199, v27, v199
	v_mul_f32_e32 v200, v28, v200
	v_mul_f32_e32 v201, v29, v201
	v_mul_f32_e32 v202, v30, v202
	v_mul_f32_e32 v203, v31, v203
	v_mul_f32_e32 v196, v8, v196
	v_mul_f32_e32 v197, v9, v197
	v_mul_f32_e32 v198, v10, v198
	v_mul_f32_e32 v199, v11, v199
	v_mul_f32_e32 v200, v12, v200
	v_mul_f32_e32 v201, v13, v201
	v_mul_f32_e32 v202, v14, v202
	v_mul_f32_e32 v203, v15, v203
	v_cvt_pk_bf16_f32 v242, v196, v197
	v_cvt_pk_bf16_f32 v243, v198, v199
	v_cvt_pk_bf16_f32 v244, v200, v201
	v_cvt_pk_bf16_f32 v245, v202, v203
	global_store_dwordx4 v167, v[242:245], s[12:13] offset:2304 sc0 sc1
	v_readlane_b32 s0, v254, 11
	s_add_i32 s2, s2, s0
	s_cmp_lt_i32 s2, s3
	s_barrier
	s_cbranch_scc1 .LBB0_1031
